# grid barrier release path one hop shorter (last XCD leader bumps every XCD generation word directly)
# speedup vs baseline: 1.0265x; 1.0023x over previous
.LBB0_70:
	s_or_b64 exec, exec, s[10:11]
	v_cvt_f32_u32_e32 v4, v1
	s_waitcnt vmcnt(0)
	v_readfirstlane_b32 s8, v3
	v_sub_u32_e32 v3, 0, v1
	v_rcp_iflag_f32_e32 v4, v4
	v_add_u32_e32 v5, s8, v2
	v_mul_f32_e32 v4, 0x4f7ffffe, v4
	v_cvt_u32_f32_e32 v4, v4
	v_mul_lo_u32 v2, v3, v4
	v_mul_hi_u32 v2, v4, v2
	v_add_u32_e32 v2, v4, v2
	v_mul_hi_u32 v2, v5, v2
	v_mul_lo_u32 v3, v2, v1
	v_sub_u32_e32 v3, v5, v3
	v_add_u32_e32 v4, 1, v2
	v_cmp_ge_u32_e32 vcc, v3, v1
	s_nop 1
	v_cndmask_b32_e32 v2, v2, v4, vcc
	v_sub_u32_e32 v4, v3, v1
	v_cndmask_b32_e32 v3, v3, v4, vcc
	v_add_u32_e32 v4, 1, v2
	v_cmp_ge_u32_e32 vcc, v3, v1
	v_add_u32_e32 v3, 1, v5
	s_nop 0
	v_cndmask_b32_e32 v2, v2, v4, vcc
	v_mul_lo_u32 v4, v1, v2
	v_add_u32_e32 v1, v4, v1
	v_cmp_ne_u32_e32 vcc, v3, v1
	s_and_saveexec_b64 s[8:9], vcc
	s_xor_b64 s[8:9], exec, s[8:9]
	s_cbranch_execz .LBB0_86
	v_mov_b32_e32 v1, 0x4000
	buffer_inv sc1
	v_mov_b32_e32 v1, 0x2000
	global_load_dword v1, v1, s[6:7] offset:1024 sc1
	s_add_u32 s14, s6, 0x2400
	s_addc_u32 s15, s7, 0
	s_waitcnt vmcnt(0)
	v_cmp_eq_u32_e32 vcc, v1, v2
	s_and_saveexec_b64 s[10:11], vcc
	s_cbranch_execz .LBB0_83
	s_add_u32 s12, s28, 0x1200
	s_addc_u32 s13, s29, 0
	s_mov_b32 s20, 1
	s_mov_b64 s[18:19], 0
	v_mov_b32_e32 v1, 0
	s_branch .LBB0_74

.LBB0_83:
	s_or_b64 exec, exec, s[10:11]
	s_mov_b64 s[12:13], exec
	v_mbcnt_lo_u32_b32 v1, s12, 0
	v_mbcnt_hi_u32_b32 v1, s13, v1
	v_cmp_eq_u32_e32 vcc, 0, v1
	s_and_saveexec_b64 s[10:11], vcc
	s_cbranch_execz .LBB0_85
	s_bcnt1_i32_b64 s12, s[12:13]
	v_mov_b32_e32 v1, 0x2000
	v_mov_b32_e32 v2, s12
	s_nop 0

.LBB0_89:
	s_or_b64 exec, exec, s[10:11]
	s_mov_b64 s[12:13], exec
	v_mbcnt_lo_u32_b32 v1, s12, 0
	v_mbcnt_hi_u32_b32 v1, s13, v1
	v_cmp_eq_u32_e32 vcc, 0, v1
	s_and_saveexec_b64 s[10:11], vcc
	s_cbranch_execz .LBB0_91
	s_bcnt1_i32_b64 s12, s[12:13]
	v_mov_b32_e32 v1, 0x2000
	v_mov_b32_e32 v2, s12
	global_atomic_add v1, v2, s[34:35] offset:1024
	v_add_u32_e32 v1, 0x100, v1
	global_atomic_add v1, v2, s[34:35] offset:1024
	v_add_u32_e32 v1, 0x100, v1
	global_atomic_add v1, v2, s[34:35] offset:1024
	v_add_u32_e32 v1, 0x100, v1
	global_atomic_add v1, v2, s[34:35] offset:1024
	v_add_u32_e32 v1, 0x100, v1
	global_atomic_add v1, v2, s[34:35] offset:1024
	v_add_u32_e32 v1, 0x100, v1
	global_atomic_add v1, v2, s[34:35] offset:1024
	v_add_u32_e32 v1, 0x100, v1
	global_atomic_add v1, v2, s[34:35] offset:1024
	v_add_u32_e32 v1, 0x100, v1
	global_atomic_add v1, v2, s[34:35] offset:1024
	v_add_u32_e32 v1, 0x100, v1
	global_atomic_add v1, v2, s[34:35] offset:1024
	v_add_u32_e32 v1, 0x100, v1
	global_atomic_add v1, v2, s[34:35] offset:1024
	v_add_u32_e32 v1, 0x100, v1
	global_atomic_add v1, v2, s[34:35] offset:1024
	v_add_u32_e32 v1, 0x100, v1
	global_atomic_add v1, v2, s[34:35] offset:1024
	v_add_u32_e32 v1, 0x100, v1
	global_atomic_add v1, v2, s[34:35] offset:1024
	v_add_u32_e32 v1, 0x100, v1
	global_atomic_add v1, v2, s[34:35] offset:1024
	v_add_u32_e32 v1, 0x100, v1
	global_atomic_add v1, v2, s[34:35] offset:1024
	v_add_u32_e32 v1, 0x100, v1
	global_atomic_add v1, v2, s[34:35] offset:1024

.LBB0_800:
	s_or_b64 exec, exec, s[10:11]
	v_cvt_f32_u32_e32 v4, v1
	s_waitcnt vmcnt(0)
	v_readfirstlane_b32 s8, v3
	v_sub_u32_e32 v3, 0, v1
	v_rcp_iflag_f32_e32 v4, v4
	v_add_u32_e32 v5, s8, v2
	v_mul_f32_e32 v4, 0x4f7ffffe, v4
	v_cvt_u32_f32_e32 v4, v4
	v_mul_lo_u32 v2, v3, v4
	v_mul_hi_u32 v2, v4, v2
	v_add_u32_e32 v2, v4, v2
	v_mul_hi_u32 v2, v5, v2
	v_mul_lo_u32 v3, v2, v1
	v_sub_u32_e32 v3, v5, v3
	v_add_u32_e32 v4, 1, v2
	v_cmp_ge_u32_e32 vcc, v3, v1
	s_nop 1
	v_cndmask_b32_e32 v2, v2, v4, vcc
	v_sub_u32_e32 v4, v3, v1
	v_cndmask_b32_e32 v3, v3, v4, vcc
	v_add_u32_e32 v4, 1, v2
	v_cmp_ge_u32_e32 vcc, v3, v1
	v_add_u32_e32 v3, 1, v5
	s_nop 0
	v_cndmask_b32_e32 v2, v2, v4, vcc
	v_mul_lo_u32 v4, v1, v2
	v_add_u32_e32 v1, v4, v1
	v_cmp_ne_u32_e32 vcc, v3, v1
	s_and_saveexec_b64 s[8:9], vcc
	s_xor_b64 s[8:9], exec, s[8:9]
	s_cbranch_execz .LBB0_816
	v_mov_b32_e32 v1, 0x4000
	buffer_inv sc1
	v_mov_b32_e32 v1, 0x2000
	global_load_dword v1, v1, s[6:7] offset:1024 sc1
	s_add_u32 s14, s6, 0x2400
	s_addc_u32 s15, s7, 0
	s_waitcnt vmcnt(0)
	v_cmp_eq_u32_e32 vcc, v1, v2
	s_and_saveexec_b64 s[10:11], vcc
	s_cbranch_execz .LBB0_813
	s_add_u32 s12, s28, 0x1200
	s_addc_u32 s13, s29, 0
	s_mov_b32 s26, 1
	s_mov_b64 s[18:19], 0
	v_mov_b32_e32 v1, 0
	s_branch .LBB0_804

.LBB0_1101:
	s_or_b64 exec, exec, s[10:11]
	v_cvt_f32_u32_e32 v3, v0
	s_waitcnt vmcnt(0)
	v_readfirstlane_b32 s8, v2
	v_sub_u32_e32 v2, 0, v0
	v_rcp_iflag_f32_e32 v3, v3
	v_add_u32_e32 v4, s8, v1
	v_mul_f32_e32 v3, 0x4f7ffffe, v3
	v_cvt_u32_f32_e32 v3, v3
	v_mul_lo_u32 v1, v2, v3
	v_mul_hi_u32 v1, v3, v1
	v_add_u32_e32 v1, v3, v1
	v_mul_hi_u32 v1, v4, v1
	v_mul_lo_u32 v2, v1, v0
	v_sub_u32_e32 v2, v4, v2
	v_add_u32_e32 v3, 1, v1
	v_cmp_ge_u32_e32 vcc, v2, v0
	s_nop 1
	v_cndmask_b32_e32 v1, v1, v3, vcc
	v_sub_u32_e32 v3, v2, v0
	v_cndmask_b32_e32 v2, v2, v3, vcc
	v_add_u32_e32 v3, 1, v1
	v_cmp_ge_u32_e32 vcc, v2, v0
	v_add_u32_e32 v2, 1, v4
	s_nop 0
	v_cndmask_b32_e32 v1, v1, v3, vcc
	v_mul_lo_u32 v3, v0, v1
	v_add_u32_e32 v0, v3, v0
	v_cmp_ne_u32_e32 vcc, v2, v0
	s_and_saveexec_b64 s[8:9], vcc
	s_xor_b64 s[8:9], exec, s[8:9]
	s_cbranch_execz .LBB0_1117
	v_mov_b32_e32 v0, 0x4000
	buffer_inv sc1
	v_mov_b32_e32 v0, 0x2000
	global_load_dword v0, v0, s[6:7] offset:1024 sc1
	s_add_u32 s14, s6, 0x2400
	s_addc_u32 s15, s7, 0
	s_waitcnt vmcnt(0)
	v_cmp_eq_u32_e32 vcc, v0, v1
	s_and_saveexec_b64 s[10:11], vcc
	s_cbranch_execz .LBB0_1114
	s_add_u32 s12, s28, 0x1200
	s_addc_u32 s13, s29, 0
	s_mov_b32 s26, 1
	s_mov_b64 s[16:17], 0
	v_mov_b32_e32 v0, 0
	s_branch .LBB0_1105

.LBB0_1114:
	s_or_b64 exec, exec, s[10:11]
	s_mov_b64 s[12:13], exec
	v_mbcnt_lo_u32_b32 v0, s12, 0
	v_mbcnt_hi_u32_b32 v0, s13, v0
	v_cmp_eq_u32_e32 vcc, 0, v0
	s_and_saveexec_b64 s[10:11], vcc
	s_cbranch_execz .LBB0_1116
	s_bcnt1_i32_b64 s12, s[12:13]
	v_mov_b32_e32 v0, 0x2000
	v_mov_b32_e32 v1, s12
	s_nop 0

.LBB0_1120:
	s_or_b64 exec, exec, s[10:11]
	s_mov_b64 s[12:13], exec
	v_mbcnt_lo_u32_b32 v0, s12, 0
	v_mbcnt_hi_u32_b32 v0, s13, v0
	v_cmp_eq_u32_e32 vcc, 0, v0
	s_and_saveexec_b64 s[10:11], vcc
	s_cbranch_execz .LBB0_1122
	s_bcnt1_i32_b64 s12, s[12:13]
	v_mov_b32_e32 v0, 0x2000
	v_mov_b32_e32 v1, s12
	global_atomic_add v0, v1, s[34:35] offset:1024
	v_add_u32_e32 v0, 0x100, v0
	global_atomic_add v0, v1, s[34:35] offset:1024
	v_add_u32_e32 v0, 0x100, v0
	global_atomic_add v0, v1, s[34:35] offset:1024
	v_add_u32_e32 v0, 0x100, v0
	global_atomic_add v0, v1, s[34:35] offset:1024
	v_add_u32_e32 v0, 0x100, v0
	global_atomic_add v0, v1, s[34:35] offset:1024
	v_add_u32_e32 v0, 0x100, v0
	global_atomic_add v0, v1, s[34:35] offset:1024
	v_add_u32_e32 v0, 0x100, v0
	global_atomic_add v0, v1, s[34:35] offset:1024
	v_add_u32_e32 v0, 0x100, v0
	global_atomic_add v0, v1, s[34:35] offset:1024
	v_add_u32_e32 v0, 0x100, v0
	global_atomic_add v0, v1, s[34:35] offset:1024
	v_add_u32_e32 v0, 0x100, v0
	global_atomic_add v0, v1, s[34:35] offset:1024
	v_add_u32_e32 v0, 0x100, v0
	global_atomic_add v0, v1, s[34:35] offset:1024
	v_add_u32_e32 v0, 0x100, v0
	global_atomic_add v0, v1, s[34:35] offset:1024
	v_add_u32_e32 v0, 0x100, v0
	global_atomic_add v0, v1, s[34:35] offset:1024
	v_add_u32_e32 v0, 0x100, v0
	global_atomic_add v0, v1, s[34:35] offset:1024
	v_add_u32_e32 v0, 0x100, v0
	global_atomic_add v0, v1, s[34:35] offset:1024
	v_add_u32_e32 v0, 0x100, v0
	global_atomic_add v0, v1, s[34:35] offset:1024
